# P6 epilogue hand-rewritten: 16 residual loads hoisted, counted vmcnt, global_* instead of flat_*
# speedup vs baseline: 1.0062x; 1.0062x over previous
; __device__ __forceinline__ u32x4 pack8(const f32x4& v0, const f32x4& v1) { u32x4 w; w.x = cvt_pk_bf16(v0[0], v0[1]); w.y = cvt_pk_bf16(v0[2], v0[3]); w.z = cvt_pk_bf16(v1[0], v1[1]); w.w = cvt_pk_bf16(v1[2], v1[3]); return w; }
; __device__ __forceinline__ void unpack8(const u32x4& g, f32x4& a, f32x4& b) { a = (f32x4){bf_lo(g.x), bf_hi(g.x), bf_lo(g.y), bf_hi(g.y)}; b = (f32x4){bf_lo(g.z), bf_hi(g.z), bf_lo(g.w), bf_hi(g.w)}; }
; __device__ __forceinline__ float sq4(const f32x4& v) { return (v[0] * v[0] + v[1] * v[1]) + (v[2] * v[2] + v[3] * v[3]); }
; #define EPI_LOOP_ROWS _Pragma("unroll") for (int ai = 0; ai < 2; ++ai) _Pragma("unroll") for (int m = 0; m < 4; ++m)
; #define EPI_LOOP_BJ _Pragma("unroll") for (int bj = 0; bj < 2; ++bj)
;     __device__ __forceinline__ void operator()(const f32x4 (&acc)[2][2][4][2], const Unit& u, int wr, int wc, int fr, int fq) const {
;         const int col0 = u.pn * BM + wc * 32 + 8 * fq, row0 = u.pm * BM + wr * 64 + fr;
;         float sv[2][4];
;         EPI_LOOP_ROWS { const int row = row0 + ai * HALF + m * 16; const size_t off = (size_t)row * 2048 + col0; float s = 0.f;
;             EPI_LOOP_BJ { f32x4 b0, b1;
;                 if (BASE_BF16) { const u32x4 bb = *(const u32x4*)((const bf16_t*)base + off + bj * HALF); unpack8(bb, b0, b1); }
;                 else { b0 = __builtin_nontemporal_load((const f32x4*)((const float*)base + off + bj * HALF)); b1 = __builtin_nontemporal_load((const f32x4*)((const float*)base + off + bj * HALF + 4)); }
;                 const f32x4 o0 = b0 + acc[ai][bj][m][0], o1 = b1 + acc[ai][bj][m][1];
;                 *(u32x4*)(outb + off + bj * HALF) = pack8(o0, o1); s += sq4(o0) + sq4(o1); }
;             s += __shfl_xor(s, 16); s += __shfl_xor(s, 32); sv[ai][m] = s; asm volatile("" ::: "memory"); }
.LBB0_902:
	v_lshl_add_u32 v146, s36, 8, v153
	v_lshl_or_b32 v148, s37, 8, v155
	v_ashrrev_i32_e32 v147, 31, v146
	v_lshlrev_b32_e32 v149, 12, v146
	v_lshl_add_u32 v149, v148, 1, v149
	v_add_u32_e32 v150, 0x10000, v149
	v_add_u32_e32 v151, 0x20000, v149
	v_add_u32_e32 v184, 0x30000, v149
	v_add_u32_e32 v185, 0x80000, v149
	v_add_u32_e32 v224, 0x90000, v149
	v_add_u32_e32 v225, 0xa0000, v149
	v_add_u32_e32 v228, 0xb0000, v149
	global_load_dwordx4 v[160:163], v149, s[8:9]
	global_load_dwordx4 v[164:167], v149, s[8:9] offset:256
	global_load_dwordx4 v[168:171], v150, s[8:9]
	global_load_dwordx4 v[172:175], v150, s[8:9] offset:256
	global_load_dwordx4 v[176:179], v151, s[8:9]
	global_load_dwordx4 v[180:183], v151, s[8:9] offset:256
	global_load_dwordx4 v[188:191], v184, s[8:9]
	global_load_dwordx4 v[192:195], v184, s[8:9] offset:256
	global_load_dwordx4 v[196:199], v185, s[8:9]
	global_load_dwordx4 v[200:203], v185, s[8:9] offset:256
	global_load_dwordx4 v[204:207], v224, s[8:9]
	global_load_dwordx4 v[208:211], v224, s[8:9] offset:256
	global_load_dwordx4 v[212:215], v225, s[8:9]
	global_load_dwordx4 v[216:219], v225, s[8:9] offset:256
	global_load_dwordx4 v[220:223], v228, s[8:9]
	global_load_dwordx4 v[232:235], v228, s[8:9] offset:256
	s_waitcnt vmcnt(15)
	v_lshlrev_b32_e32 v236, 16, v160
	v_and_b32_e32 v237, 0xffff0000, v160
	v_lshlrev_b32_e32 v238, 16, v161
	v_and_b32_e32 v239, 0xffff0000, v161
	v_lshlrev_b32_e32 v240, 16, v162
	v_and_b32_e32 v241, 0xffff0000, v162
	v_lshlrev_b32_e32 v242, 16, v163
	v_and_b32_e32 v243, 0xffff0000, v163
	v_add_f32_e32 v124, v124, v236
	v_add_f32_e32 v125, v125, v237
	v_add_f32_e32 v126, v126, v238
	v_add_f32_e32 v127, v127, v239
	v_add_f32_e32 v120, v120, v240
	v_add_f32_e32 v121, v121, v241
	v_add_f32_e32 v122, v122, v242
	v_add_f32_e32 v123, v123, v243
	v_cvt_pk_bf16_f32 v160, v124, v125
	v_cvt_pk_bf16_f32 v161, v126, v127
	v_cvt_pk_bf16_f32 v162, v120, v121
	v_cvt_pk_bf16_f32 v163, v122, v123
	global_store_dwordx4 v149, v[160:163], s[8:9]
	v_mul_f32_e32 v244, v124, v124
	v_mul_f32_e32 v236, v120, v120
	v_fmac_f32_e32 v244, v125, v125
	v_fmac_f32_e32 v236, v121, v121
	v_fmac_f32_e32 v244, v126, v126
	v_fmac_f32_e32 v236, v122, v122
	v_fmac_f32_e32 v244, v127, v127
	v_fmac_f32_e32 v236, v123, v123
	v_add_f32_e32 v244, v244, v236
	s_waitcnt vmcnt(15)
	v_lshlrev_b32_e32 v236, 16, v164
	v_and_b32_e32 v237, 0xffff0000, v164
	v_lshlrev_b32_e32 v238, 16, v165
	v_and_b32_e32 v239, 0xffff0000, v165
	v_lshlrev_b32_e32 v240, 16, v166
	v_and_b32_e32 v241, 0xffff0000, v166
	v_lshlrev_b32_e32 v242, 16, v167
	v_and_b32_e32 v243, 0xffff0000, v167
	v_add_f32_e32 v116, v116, v236
	v_add_f32_e32 v117, v117, v237
	v_add_f32_e32 v118, v118, v238
	v_add_f32_e32 v119, v119, v239
	v_add_f32_e32 v112, v112, v240
	v_add_f32_e32 v113, v113, v241
	v_add_f32_e32 v114, v114, v242
	v_add_f32_e32 v115, v115, v243
	v_cvt_pk_bf16_f32 v164, v116, v117
	v_cvt_pk_bf16_f32 v165, v118, v119
	v_cvt_pk_bf16_f32 v166, v112, v113
	v_cvt_pk_bf16_f32 v167, v114, v115
	global_store_dwordx4 v149, v[164:167], s[8:9] offset:256
	v_mul_f32_e32 v229, v116, v116
	v_mul_f32_e32 v236, v112, v112
	v_fmac_f32_e32 v229, v117, v117
	v_fmac_f32_e32 v236, v113, v113
	v_fmac_f32_e32 v229, v118, v118
	v_fmac_f32_e32 v236, v114, v114
	v_fmac_f32_e32 v229, v119, v119
	v_fmac_f32_e32 v236, v115, v115
	v_add_f32_e32 v229, v229, v236
	v_add_f32_e32 v244, v244, v229
	s_waitcnt vmcnt(15)
	v_lshlrev_b32_e32 v236, 16, v168
	v_and_b32_e32 v237, 0xffff0000, v168
	v_lshlrev_b32_e32 v238, 16, v169
	v_and_b32_e32 v239, 0xffff0000, v169
	v_lshlrev_b32_e32 v240, 16, v170
	v_and_b32_e32 v241, 0xffff0000, v170
	v_lshlrev_b32_e32 v242, 16, v171
	v_and_b32_e32 v243, 0xffff0000, v171
	v_add_f32_e32 v108, v108, v236
	v_add_f32_e32 v109, v109, v237
	v_add_f32_e32 v110, v110, v238
	v_add_f32_e32 v111, v111, v239
	v_add_f32_e32 v104, v104, v240
	v_add_f32_e32 v105, v105, v241
	v_add_f32_e32 v106, v106, v242
	v_add_f32_e32 v107, v107, v243
	v_cvt_pk_bf16_f32 v168, v108, v109
	v_cvt_pk_bf16_f32 v169, v110, v111
	v_cvt_pk_bf16_f32 v170, v104, v105
	v_cvt_pk_bf16_f32 v171, v106, v107
	global_store_dwordx4 v150, v[168:171], s[8:9]
	v_mul_f32_e32 v245, v108, v108
	v_mul_f32_e32 v236, v104, v104
	v_fmac_f32_e32 v245, v109, v109
	v_fmac_f32_e32 v236, v105, v105
	v_fmac_f32_e32 v245, v110, v110
	v_fmac_f32_e32 v236, v106, v106
	v_fmac_f32_e32 v245, v111, v111
	v_fmac_f32_e32 v236, v107, v107
	v_add_f32_e32 v245, v245, v236
	s_waitcnt vmcnt(15)
	v_lshlrev_b32_e32 v236, 16, v172
	v_and_b32_e32 v237, 0xffff0000, v172
	v_lshlrev_b32_e32 v238, 16, v173
	v_and_b32_e32 v239, 0xffff0000, v173
	v_lshlrev_b32_e32 v240, 16, v174
	v_and_b32_e32 v241, 0xffff0000, v174
	v_lshlrev_b32_e32 v242, 16, v175
	v_and_b32_e32 v243, 0xffff0000, v175
	v_add_f32_e32 v100, v100, v236
	v_add_f32_e32 v101, v101, v237
	v_add_f32_e32 v102, v102, v238
	v_add_f32_e32 v103, v103, v239
	v_add_f32_e32 v96, v96, v240
	v_add_f32_e32 v97, v97, v241
	v_add_f32_e32 v98, v98, v242
	v_add_f32_e32 v99, v99, v243
	v_cvt_pk_bf16_f32 v172, v100, v101
	v_cvt_pk_bf16_f32 v173, v102, v103
	v_cvt_pk_bf16_f32 v174, v96, v97
	v_cvt_pk_bf16_f32 v175, v98, v99
	global_store_dwordx4 v150, v[172:175], s[8:9] offset:256
	v_mul_f32_e32 v229, v100, v100
	v_mul_f32_e32 v236, v96, v96
	v_fmac_f32_e32 v229, v101, v101
	v_fmac_f32_e32 v236, v97, v97
	v_fmac_f32_e32 v229, v102, v102
	v_fmac_f32_e32 v236, v98, v98
	v_fmac_f32_e32 v229, v103, v103
	v_fmac_f32_e32 v236, v99, v99
	v_add_f32_e32 v229, v229, v236
	v_add_f32_e32 v245, v245, v229
	s_waitcnt vmcnt(15)
; __device__ __forceinline__ u32x4 pack8(const f32x4& v0, const f32x4& v1) { u32x4 w; w.x = cvt_pk_bf16(v0[0], v0[1]); w.y = cvt_pk_bf16(v0[2], v0[3]); w.z = cvt_pk_bf16(v1[0], v1[1]); w.w = cvt_pk_bf16(v1[2], v1[3]); return w; }
; __device__ __forceinline__ void unpack8(const u32x4& g, f32x4& a, f32x4& b) { a = (f32x4){bf_lo(g.x), bf_hi(g.x), bf_lo(g.y), bf_hi(g.y)}; b = (f32x4){bf_lo(g.z), bf_hi(g.z), bf_lo(g.w), bf_hi(g.w)}; }
; __device__ __forceinline__ float sq4(const f32x4& v) { return (v[0] * v[0] + v[1] * v[1]) + (v[2] * v[2] + v[3] * v[3]); }
; #define EPI_LOOP_ROWS _Pragma("unroll") for (int ai = 0; ai < 2; ++ai) _Pragma("unroll") for (int m = 0; m < 4; ++m)
; #define EPI_LOOP_BJ _Pragma("unroll") for (int bj = 0; bj < 2; ++bj)
;     __device__ __forceinline__ void operator()(const f32x4 (&acc)[2][2][4][2], const Unit& u, int wr, int wc, int fr, int fq) const {
;     ...
;         EPI_LOOP_ROWS { const int row = row0 + ai * HALF + m * 16; const size_t off = (size_t)row * 2048 + col0; float s = 0.f;
;             EPI_LOOP_BJ { f32x4 b0, b1;
;                 if (BASE_BF16) { const u32x4 bb = *(const u32x4*)((const bf16_t*)base + off + bj * HALF); unpack8(bb, b0, b1); }
;                 else { b0 = __builtin_nontemporal_load((const f32x4*)((const float*)base + off + bj * HALF)); b1 = __builtin_nontemporal_load((const f32x4*)((const float*)base + off + bj * HALF + 4)); }
;                 const f32x4 o0 = b0 + acc[ai][bj][m][0], o1 = b1 + acc[ai][bj][m][1];
;                 *(u32x4*)(outb + off + bj * HALF) = pack8(o0, o1); s += sq4(o0) + sq4(o1); }
	v_lshlrev_b32_e32 v236, 16, v176
	v_and_b32_e32 v237, 0xffff0000, v176
	v_lshlrev_b32_e32 v238, 16, v177
	v_and_b32_e32 v239, 0xffff0000, v177
	v_lshlrev_b32_e32 v240, 16, v178
	v_and_b32_e32 v241, 0xffff0000, v178
	v_lshlrev_b32_e32 v242, 16, v179
	v_and_b32_e32 v243, 0xffff0000, v179
	v_add_f32_e32 v92, v92, v236
	v_add_f32_e32 v93, v93, v237
	v_add_f32_e32 v94, v94, v238
	v_add_f32_e32 v95, v95, v239
	v_add_f32_e32 v88, v88, v240
	v_add_f32_e32 v89, v89, v241
	v_add_f32_e32 v90, v90, v242
	v_add_f32_e32 v91, v91, v243
	v_cvt_pk_bf16_f32 v176, v92, v93
	v_cvt_pk_bf16_f32 v177, v94, v95
	v_cvt_pk_bf16_f32 v178, v88, v89
	v_cvt_pk_bf16_f32 v179, v90, v91
	global_store_dwordx4 v151, v[176:179], s[8:9]
	v_mul_f32_e32 v246, v92, v92
	v_mul_f32_e32 v236, v88, v88
	v_fmac_f32_e32 v246, v93, v93
	v_fmac_f32_e32 v236, v89, v89
	v_fmac_f32_e32 v246, v94, v94
	v_fmac_f32_e32 v236, v90, v90
	v_fmac_f32_e32 v246, v95, v95
	v_fmac_f32_e32 v236, v91, v91
	v_add_f32_e32 v246, v246, v236
	s_waitcnt vmcnt(15)
	v_lshlrev_b32_e32 v236, 16, v180
	v_and_b32_e32 v237, 0xffff0000, v180
	v_lshlrev_b32_e32 v238, 16, v181
	v_and_b32_e32 v239, 0xffff0000, v181
	v_lshlrev_b32_e32 v240, 16, v182
	v_and_b32_e32 v241, 0xffff0000, v182
	v_lshlrev_b32_e32 v242, 16, v183
	v_and_b32_e32 v243, 0xffff0000, v183
	v_add_f32_e32 v84, v84, v236
	v_add_f32_e32 v85, v85, v237
	v_add_f32_e32 v86, v86, v238
	v_add_f32_e32 v87, v87, v239
	v_add_f32_e32 v80, v80, v240
	v_add_f32_e32 v81, v81, v241
	v_add_f32_e32 v82, v82, v242
	v_add_f32_e32 v83, v83, v243
	v_cvt_pk_bf16_f32 v180, v84, v85
	v_cvt_pk_bf16_f32 v181, v86, v87
	v_cvt_pk_bf16_f32 v182, v80, v81
	v_cvt_pk_bf16_f32 v183, v82, v83
	global_store_dwordx4 v151, v[180:183], s[8:9] offset:256
	v_mul_f32_e32 v229, v84, v84
	v_mul_f32_e32 v236, v80, v80
	v_fmac_f32_e32 v229, v85, v85
	v_fmac_f32_e32 v236, v81, v81
	v_fmac_f32_e32 v229, v86, v86
	v_fmac_f32_e32 v236, v82, v82
	v_fmac_f32_e32 v229, v87, v87
	v_fmac_f32_e32 v236, v83, v83
	v_add_f32_e32 v229, v229, v236
	v_add_f32_e32 v246, v246, v229
	s_waitcnt vmcnt(15)
	v_lshlrev_b32_e32 v236, 16, v188
	v_and_b32_e32 v237, 0xffff0000, v188
	v_lshlrev_b32_e32 v238, 16, v189
	v_and_b32_e32 v239, 0xffff0000, v189
	v_lshlrev_b32_e32 v240, 16, v190
	v_and_b32_e32 v241, 0xffff0000, v190
	v_lshlrev_b32_e32 v242, 16, v191
	v_and_b32_e32 v243, 0xffff0000, v191
	v_add_f32_e32 v76, v76, v236
	v_add_f32_e32 v77, v77, v237
	v_add_f32_e32 v78, v78, v238
	v_add_f32_e32 v79, v79, v239
	v_add_f32_e32 v72, v72, v240
	v_add_f32_e32 v73, v73, v241
	v_add_f32_e32 v74, v74, v242
	v_add_f32_e32 v75, v75, v243
	v_cvt_pk_bf16_f32 v188, v76, v77
	v_cvt_pk_bf16_f32 v189, v78, v79
	v_cvt_pk_bf16_f32 v190, v72, v73
	v_cvt_pk_bf16_f32 v191, v74, v75
	global_store_dwordx4 v184, v[188:191], s[8:9]
	v_mul_f32_e32 v247, v76, v76
	v_mul_f32_e32 v236, v72, v72
	v_fmac_f32_e32 v247, v77, v77
	v_fmac_f32_e32 v236, v73, v73
	v_fmac_f32_e32 v247, v78, v78
	v_fmac_f32_e32 v236, v74, v74
	v_fmac_f32_e32 v247, v79, v79
	v_fmac_f32_e32 v236, v75, v75
	v_add_f32_e32 v247, v247, v236
	s_waitcnt vmcnt(15)
	v_lshlrev_b32_e32 v236, 16, v192
	v_and_b32_e32 v237, 0xffff0000, v192
	v_lshlrev_b32_e32 v238, 16, v193
	v_and_b32_e32 v239, 0xffff0000, v193
	v_lshlrev_b32_e32 v240, 16, v194
	v_and_b32_e32 v241, 0xffff0000, v194
	v_lshlrev_b32_e32 v242, 16, v195
	v_and_b32_e32 v243, 0xffff0000, v195
	v_add_f32_e32 v68, v68, v236
	v_add_f32_e32 v69, v69, v237
	v_add_f32_e32 v70, v70, v238
	v_add_f32_e32 v71, v71, v239
	v_add_f32_e32 v64, v64, v240
	v_add_f32_e32 v65, v65, v241
	v_add_f32_e32 v66, v66, v242
	v_add_f32_e32 v67, v67, v243
	v_cvt_pk_bf16_f32 v192, v68, v69
	v_cvt_pk_bf16_f32 v193, v70, v71
	v_cvt_pk_bf16_f32 v194, v64, v65
	v_cvt_pk_bf16_f32 v195, v66, v67
	global_store_dwordx4 v184, v[192:195], s[8:9] offset:256
	v_mul_f32_e32 v229, v68, v68
	v_mul_f32_e32 v236, v64, v64
	v_fmac_f32_e32 v229, v69, v69
	v_fmac_f32_e32 v236, v65, v65
	v_fmac_f32_e32 v229, v70, v70
	v_fmac_f32_e32 v236, v66, v66
	v_fmac_f32_e32 v229, v71, v71
	v_fmac_f32_e32 v236, v67, v67
	v_add_f32_e32 v229, v229, v236
	v_add_f32_e32 v247, v247, v229
	s_waitcnt vmcnt(15)
	v_lshlrev_b32_e32 v236, 16, v196
	v_and_b32_e32 v237, 0xffff0000, v196
	v_lshlrev_b32_e32 v238, 16, v197
	v_and_b32_e32 v239, 0xffff0000, v197
	v_lshlrev_b32_e32 v240, 16, v198
	v_and_b32_e32 v241, 0xffff0000, v198
	v_lshlrev_b32_e32 v242, 16, v199
	v_and_b32_e32 v243, 0xffff0000, v199
	v_add_f32_e32 v60, v60, v236
	v_add_f32_e32 v61, v61, v237
	v_add_f32_e32 v62, v62, v238
	v_add_f32_e32 v63, v63, v239
	v_add_f32_e32 v56, v56, v240
	v_add_f32_e32 v57, v57, v241
	v_add_f32_e32 v58, v58, v242
	v_add_f32_e32 v59, v59, v243
	v_cvt_pk_bf16_f32 v196, v60, v61
	v_cvt_pk_bf16_f32 v197, v62, v63
	v_cvt_pk_bf16_f32 v198, v56, v57
	v_cvt_pk_bf16_f32 v199, v58, v59
	global_store_dwordx4 v185, v[196:199], s[8:9]
	v_mul_f32_e32 v248, v60, v60
	v_mul_f32_e32 v236, v56, v56
	v_fmac_f32_e32 v248, v61, v61
	v_fmac_f32_e32 v236, v57, v57
	v_fmac_f32_e32 v248, v62, v62
	v_fmac_f32_e32 v236, v58, v58
	v_fmac_f32_e32 v248, v63, v63
	v_fmac_f32_e32 v236, v59, v59
	v_add_f32_e32 v248, v248, v236
	s_waitcnt vmcnt(15)
; __device__ __forceinline__ u32x4 pack8(const f32x4& v0, const f32x4& v1) { u32x4 w; w.x = cvt_pk_bf16(v0[0], v0[1]); w.y = cvt_pk_bf16(v0[2], v0[3]); w.z = cvt_pk_bf16(v1[0], v1[1]); w.w = cvt_pk_bf16(v1[2], v1[3]); return w; }
; __device__ __forceinline__ void unpack8(const u32x4& g, f32x4& a, f32x4& b) { a = (f32x4){bf_lo(g.x), bf_hi(g.x), bf_lo(g.y), bf_hi(g.y)}; b = (f32x4){bf_lo(g.z), bf_hi(g.z), bf_lo(g.w), bf_hi(g.w)}; }
; __device__ __forceinline__ float sq4(const f32x4& v) { return (v[0] * v[0] + v[1] * v[1]) + (v[2] * v[2] + v[3] * v[3]); }
; #define EPI_LOOP_ROWS _Pragma("unroll") for (int ai = 0; ai < 2; ++ai) _Pragma("unroll") for (int m = 0; m < 4; ++m)
; #define EPI_LOOP_BJ _Pragma("unroll") for (int bj = 0; bj < 2; ++bj)
;     __device__ __forceinline__ void operator()(const f32x4 (&acc)[2][2][4][2], const Unit& u, int wr, int wc, int fr, int fq) const {
;     ...
;         EPI_LOOP_ROWS { const int row = row0 + ai * HALF + m * 16; const size_t off = (size_t)row * 2048 + col0; float s = 0.f;
;             EPI_LOOP_BJ { f32x4 b0, b1;
;                 if (BASE_BF16) { const u32x4 bb = *(const u32x4*)((const bf16_t*)base + off + bj * HALF); unpack8(bb, b0, b1); }
;                 else { b0 = __builtin_nontemporal_load((const f32x4*)((const float*)base + off + bj * HALF)); b1 = __builtin_nontemporal_load((const f32x4*)((const float*)base + off + bj * HALF + 4)); }
;                 const f32x4 o0 = b0 + acc[ai][bj][m][0], o1 = b1 + acc[ai][bj][m][1];
;                 *(u32x4*)(outb + off + bj * HALF) = pack8(o0, o1); s += sq4(o0) + sq4(o1); }
	v_lshlrev_b32_e32 v236, 16, v200
	v_and_b32_e32 v237, 0xffff0000, v200
	v_lshlrev_b32_e32 v238, 16, v201
	v_and_b32_e32 v239, 0xffff0000, v201
	v_lshlrev_b32_e32 v240, 16, v202
	v_and_b32_e32 v241, 0xffff0000, v202
	v_lshlrev_b32_e32 v242, 16, v203
	v_and_b32_e32 v243, 0xffff0000, v203
	v_add_f32_e32 v52, v52, v236
	v_add_f32_e32 v53, v53, v237
	v_add_f32_e32 v54, v54, v238
	v_add_f32_e32 v55, v55, v239
	v_add_f32_e32 v48, v48, v240
	v_add_f32_e32 v49, v49, v241
	v_add_f32_e32 v50, v50, v242
	v_add_f32_e32 v51, v51, v243
	v_cvt_pk_bf16_f32 v200, v52, v53
	v_cvt_pk_bf16_f32 v201, v54, v55
	v_cvt_pk_bf16_f32 v202, v48, v49
	v_cvt_pk_bf16_f32 v203, v50, v51
	global_store_dwordx4 v185, v[200:203], s[8:9] offset:256
	v_mul_f32_e32 v229, v52, v52
	v_mul_f32_e32 v236, v48, v48
	v_fmac_f32_e32 v229, v53, v53
	v_fmac_f32_e32 v236, v49, v49
	v_fmac_f32_e32 v229, v54, v54
	v_fmac_f32_e32 v236, v50, v50
	v_fmac_f32_e32 v229, v55, v55
	v_fmac_f32_e32 v236, v51, v51
	v_add_f32_e32 v229, v229, v236
	v_add_f32_e32 v248, v248, v229
	s_waitcnt vmcnt(15)
	v_lshlrev_b32_e32 v236, 16, v204
	v_and_b32_e32 v237, 0xffff0000, v204
	v_lshlrev_b32_e32 v238, 16, v205
	v_and_b32_e32 v239, 0xffff0000, v205
	v_lshlrev_b32_e32 v240, 16, v206
	v_and_b32_e32 v241, 0xffff0000, v206
	v_lshlrev_b32_e32 v242, 16, v207
	v_and_b32_e32 v243, 0xffff0000, v207
	v_add_f32_e32 v44, v44, v236
	v_add_f32_e32 v45, v45, v237
	v_add_f32_e32 v46, v46, v238
	v_add_f32_e32 v47, v47, v239
	v_add_f32_e32 v40, v40, v240
	v_add_f32_e32 v41, v41, v241
	v_add_f32_e32 v42, v42, v242
	v_add_f32_e32 v43, v43, v243
	v_cvt_pk_bf16_f32 v204, v44, v45
	v_cvt_pk_bf16_f32 v205, v46, v47
	v_cvt_pk_bf16_f32 v206, v40, v41
	v_cvt_pk_bf16_f32 v207, v42, v43
	global_store_dwordx4 v224, v[204:207], s[8:9]
	v_mul_f32_e32 v249, v44, v44
	v_mul_f32_e32 v236, v40, v40
	v_fmac_f32_e32 v249, v45, v45
	v_fmac_f32_e32 v236, v41, v41
	v_fmac_f32_e32 v249, v46, v46
	v_fmac_f32_e32 v236, v42, v42
	v_fmac_f32_e32 v249, v47, v47
	v_fmac_f32_e32 v236, v43, v43
	v_add_f32_e32 v249, v249, v236
	s_waitcnt vmcnt(15)
	v_lshlrev_b32_e32 v236, 16, v208
	v_and_b32_e32 v237, 0xffff0000, v208
	v_lshlrev_b32_e32 v238, 16, v209
	v_and_b32_e32 v239, 0xffff0000, v209
	v_lshlrev_b32_e32 v240, 16, v210
	v_and_b32_e32 v241, 0xffff0000, v210
	v_lshlrev_b32_e32 v242, 16, v211
	v_and_b32_e32 v243, 0xffff0000, v211
	v_add_f32_e32 v36, v36, v236
	v_add_f32_e32 v37, v37, v237
	v_add_f32_e32 v38, v38, v238
	v_add_f32_e32 v39, v39, v239
	v_add_f32_e32 v32, v32, v240
	v_add_f32_e32 v33, v33, v241
	v_add_f32_e32 v34, v34, v242
	v_add_f32_e32 v35, v35, v243
	v_cvt_pk_bf16_f32 v208, v36, v37
	v_cvt_pk_bf16_f32 v209, v38, v39
	v_cvt_pk_bf16_f32 v210, v32, v33
	v_cvt_pk_bf16_f32 v211, v34, v35
	global_store_dwordx4 v224, v[208:211], s[8:9] offset:256
	v_mul_f32_e32 v229, v36, v36
	v_mul_f32_e32 v236, v32, v32
	v_fmac_f32_e32 v229, v37, v37
	v_fmac_f32_e32 v236, v33, v33
	v_fmac_f32_e32 v229, v38, v38
	v_fmac_f32_e32 v236, v34, v34
	v_fmac_f32_e32 v229, v39, v39
	v_fmac_f32_e32 v236, v35, v35
	v_add_f32_e32 v229, v229, v236
	v_add_f32_e32 v249, v249, v229
	s_waitcnt vmcnt(15)
	v_lshlrev_b32_e32 v236, 16, v212
	v_and_b32_e32 v237, 0xffff0000, v212
	v_lshlrev_b32_e32 v238, 16, v213
	v_and_b32_e32 v239, 0xffff0000, v213
	v_lshlrev_b32_e32 v240, 16, v214
	v_and_b32_e32 v241, 0xffff0000, v214
	v_lshlrev_b32_e32 v242, 16, v215
	v_and_b32_e32 v243, 0xffff0000, v215
	v_add_f32_e32 v28, v28, v236
	v_add_f32_e32 v29, v29, v237
	v_add_f32_e32 v30, v30, v238
	v_add_f32_e32 v31, v31, v239
	v_add_f32_e32 v24, v24, v240
	v_add_f32_e32 v25, v25, v241
	v_add_f32_e32 v26, v26, v242
	v_add_f32_e32 v27, v27, v243
	v_cvt_pk_bf16_f32 v212, v28, v29
	v_cvt_pk_bf16_f32 v213, v30, v31
	v_cvt_pk_bf16_f32 v214, v24, v25
	v_cvt_pk_bf16_f32 v215, v26, v27
	global_store_dwordx4 v225, v[212:215], s[8:9]
	v_mul_f32_e32 v250, v28, v28
	v_mul_f32_e32 v236, v24, v24
	v_fmac_f32_e32 v250, v29, v29
	v_fmac_f32_e32 v236, v25, v25
	v_fmac_f32_e32 v250, v30, v30
	v_fmac_f32_e32 v236, v26, v26
	v_fmac_f32_e32 v250, v31, v31
	v_fmac_f32_e32 v236, v27, v27
	v_add_f32_e32 v250, v250, v236
	s_waitcnt vmcnt(15)
; __device__ __forceinline__ u32x4 pack8(const f32x4& v0, const f32x4& v1) { u32x4 w; w.x = cvt_pk_bf16(v0[0], v0[1]); w.y = cvt_pk_bf16(v0[2], v0[3]); w.z = cvt_pk_bf16(v1[0], v1[1]); w.w = cvt_pk_bf16(v1[2], v1[3]); return w; }
; __device__ __forceinline__ void unpack8(const u32x4& g, f32x4& a, f32x4& b) { a = (f32x4){bf_lo(g.x), bf_hi(g.x), bf_lo(g.y), bf_hi(g.y)}; b = (f32x4){bf_lo(g.z), bf_hi(g.z), bf_lo(g.w), bf_hi(g.w)}; }
; __device__ __forceinline__ float sq4(const f32x4& v) { return (v[0] * v[0] + v[1] * v[1]) + (v[2] * v[2] + v[3] * v[3]); }
; #define EPI_LOOP_ROWS _Pragma("unroll") for (int ai = 0; ai < 2; ++ai) _Pragma("unroll") for (int m = 0; m < 4; ++m)
; #define EPI_LOOP_BJ _Pragma("unroll") for (int bj = 0; bj < 2; ++bj)
;     __device__ __forceinline__ void operator()(const f32x4 (&acc)[2][2][4][2], const Unit& u, int wr, int wc, int fr, int fq) const {
;     ...
;         EPI_LOOP_ROWS { const int row = row0 + ai * HALF + m * 16; const size_t off = (size_t)row * 2048 + col0; float s = 0.f;
;             EPI_LOOP_BJ { f32x4 b0, b1;
;                 if (BASE_BF16) { const u32x4 bb = *(const u32x4*)((const bf16_t*)base + off + bj * HALF); unpack8(bb, b0, b1); }
;                 else { b0 = __builtin_nontemporal_load((const f32x4*)((const float*)base + off + bj * HALF)); b1 = __builtin_nontemporal_load((const f32x4*)((const float*)base + off + bj * HALF + 4)); }
;                 const f32x4 o0 = b0 + acc[ai][bj][m][0], o1 = b1 + acc[ai][bj][m][1];
;                 *(u32x4*)(outb + off + bj * HALF) = pack8(o0, o1); s += sq4(o0) + sq4(o1); }
;             s += __shfl_xor(s, 16); s += __shfl_xor(s, 32); sv[ai][m] = s; asm volatile("" ::: "memory"); }
; #pragma unroll
;         for (int ai = 0; ai < 2; ++ai) { const float t = fq == 0 ? sv[ai][0] : fq == 1 ? sv[ai][1] : fq == 2 ? sv[ai][2] : sv[ai][3]; unsafeAtomicAdd(ss + row0 + ai * HALF + fq * 16, t); }
;     }
	v_lshlrev_b32_e32 v236, 16, v216
	v_and_b32_e32 v237, 0xffff0000, v216
	v_lshlrev_b32_e32 v238, 16, v217
	v_and_b32_e32 v239, 0xffff0000, v217
	v_lshlrev_b32_e32 v240, 16, v218
	v_and_b32_e32 v241, 0xffff0000, v218
	v_lshlrev_b32_e32 v242, 16, v219
	v_and_b32_e32 v243, 0xffff0000, v219
	v_add_f32_e32 v20, v20, v236
	v_add_f32_e32 v21, v21, v237
	v_add_f32_e32 v22, v22, v238
	v_add_f32_e32 v23, v23, v239
	v_add_f32_e32 v16, v16, v240
	v_add_f32_e32 v17, v17, v241
	v_add_f32_e32 v18, v18, v242
	v_add_f32_e32 v19, v19, v243
	v_cvt_pk_bf16_f32 v216, v20, v21
	v_cvt_pk_bf16_f32 v217, v22, v23
	v_cvt_pk_bf16_f32 v218, v16, v17
	v_cvt_pk_bf16_f32 v219, v18, v19
	global_store_dwordx4 v225, v[216:219], s[8:9] offset:256
	v_mul_f32_e32 v229, v20, v20
	v_mul_f32_e32 v236, v16, v16
	v_fmac_f32_e32 v229, v21, v21
	v_fmac_f32_e32 v236, v17, v17
	v_fmac_f32_e32 v229, v22, v22
	v_fmac_f32_e32 v236, v18, v18
	v_fmac_f32_e32 v229, v23, v23
	v_fmac_f32_e32 v236, v19, v19
	v_add_f32_e32 v229, v229, v236
	v_add_f32_e32 v250, v250, v229
	s_waitcnt vmcnt(15)
	v_lshlrev_b32_e32 v236, 16, v220
	v_and_b32_e32 v237, 0xffff0000, v220
	v_lshlrev_b32_e32 v238, 16, v221
	v_and_b32_e32 v239, 0xffff0000, v221
	v_lshlrev_b32_e32 v240, 16, v222
	v_and_b32_e32 v241, 0xffff0000, v222
	v_lshlrev_b32_e32 v242, 16, v223
	v_and_b32_e32 v243, 0xffff0000, v223
	v_add_f32_e32 v12, v12, v236
	v_add_f32_e32 v13, v13, v237
	v_add_f32_e32 v14, v14, v238
	v_add_f32_e32 v15, v15, v239
	v_add_f32_e32 v8, v8, v240
	v_add_f32_e32 v9, v9, v241
	v_add_f32_e32 v10, v10, v242
	v_add_f32_e32 v11, v11, v243
	v_cvt_pk_bf16_f32 v220, v12, v13
	v_cvt_pk_bf16_f32 v221, v14, v15
	v_cvt_pk_bf16_f32 v222, v8, v9
	v_cvt_pk_bf16_f32 v223, v10, v11
	global_store_dwordx4 v228, v[220:223], s[8:9]
	v_mul_f32_e32 v251, v12, v12
	v_mul_f32_e32 v236, v8, v8
	v_fmac_f32_e32 v251, v13, v13
	v_fmac_f32_e32 v236, v9, v9
	v_fmac_f32_e32 v251, v14, v14
	v_fmac_f32_e32 v236, v10, v10
	v_fmac_f32_e32 v251, v15, v15
	v_fmac_f32_e32 v236, v11, v11
	v_add_f32_e32 v251, v251, v236
	s_waitcnt vmcnt(15)
	v_lshlrev_b32_e32 v236, 16, v232
	v_and_b32_e32 v237, 0xffff0000, v232
	v_lshlrev_b32_e32 v238, 16, v233
	v_and_b32_e32 v239, 0xffff0000, v233
	v_lshlrev_b32_e32 v240, 16, v234
	v_and_b32_e32 v241, 0xffff0000, v234
	v_lshlrev_b32_e32 v242, 16, v235
	v_and_b32_e32 v243, 0xffff0000, v235
	v_add_f32_e32 v4, v4, v236
	v_add_f32_e32 v5, v5, v237
	v_add_f32_e32 v6, v6, v238
	v_add_f32_e32 v7, v7, v239
	v_add_f32_e32 v0, v0, v240
	v_add_f32_e32 v1, v1, v241
	v_add_f32_e32 v2, v2, v242
	v_add_f32_e32 v3, v3, v243
	v_cvt_pk_bf16_f32 v232, v4, v5
	v_cvt_pk_bf16_f32 v233, v6, v7
	v_cvt_pk_bf16_f32 v234, v0, v1
	v_cvt_pk_bf16_f32 v235, v2, v3
	global_store_dwordx4 v228, v[232:235], s[8:9] offset:256
	v_mul_f32_e32 v229, v4, v4
	v_mul_f32_e32 v236, v0, v0
	v_fmac_f32_e32 v229, v5, v5
	v_fmac_f32_e32 v236, v1, v1
	v_fmac_f32_e32 v229, v6, v6
	v_fmac_f32_e32 v236, v2, v2
	v_fmac_f32_e32 v229, v7, v7
	v_fmac_f32_e32 v236, v3, v3
	v_add_f32_e32 v229, v229, v236
	v_add_f32_e32 v251, v251, v229
	ds_bpermute_b32 v236, v187, v244
	ds_bpermute_b32 v237, v187, v245
	ds_bpermute_b32 v238, v187, v246
	ds_bpermute_b32 v239, v187, v247
	ds_bpermute_b32 v240, v187, v248
	ds_bpermute_b32 v241, v187, v249
	ds_bpermute_b32 v242, v187, v250
	ds_bpermute_b32 v243, v187, v251
	s_waitcnt lgkmcnt(0)
	v_add_f32_e32 v244, v244, v236
	v_add_f32_e32 v245, v245, v237
	v_add_f32_e32 v246, v246, v238
	v_add_f32_e32 v247, v247, v239
	v_add_f32_e32 v248, v248, v240
	v_add_f32_e32 v249, v249, v241
	v_add_f32_e32 v250, v250, v242
	v_add_f32_e32 v251, v251, v243
	ds_bpermute_b32 v236, v186, v244
	ds_bpermute_b32 v237, v186, v245
	ds_bpermute_b32 v238, v186, v246
	ds_bpermute_b32 v239, v186, v247
	ds_bpermute_b32 v240, v186, v248
	ds_bpermute_b32 v241, v186, v249
	ds_bpermute_b32 v242, v186, v250
	ds_bpermute_b32 v243, v186, v251
	s_waitcnt lgkmcnt(0)
	v_add_f32_e32 v244, v244, v236
	v_add_f32_e32 v245, v245, v237
	v_add_f32_e32 v246, v246, v238
	v_add_f32_e32 v247, v247, v239
	v_add_f32_e32 v248, v248, v240
	v_add_f32_e32 v249, v249, v241
	v_add_f32_e32 v250, v250, v242
	v_add_f32_e32 v251, v251, v243
	v_cmp_eq_u32_e64 s[36:37], 1, v152
	v_cmp_eq_u32_e64 s[38:39], 2, v152
	v_cmp_eq_u32_e32 vcc, 3, v152
	v_lshl_add_u64 v[236:237], v[146:147], 2, v[136:137]
	s_nop 0
	v_cndmask_b32_e64 v238, v244, v245, s[36:37]
	v_cndmask_b32_e64 v238, v238, v246, s[38:39]
	v_cndmask_b32_e32 v238, v238, v247, vcc
	global_atomic_add_f32 v[236:237], v238, off
	v_cndmask_b32_e64 v239, v248, v249, s[36:37]
	v_cndmask_b32_e64 v239, v239, v250, s[38:39]
	v_cndmask_b32_e32 v239, v239, v251, vcc
	global_atomic_add_f32 v[236:237], v239, off offset:512
	s_andn2_b64 vcc, exec, s[6:7]
	s_mov_b64 s[6:7], -1
	s_cbranch_vccnz .LBB0_890
	s_andn2_b64 vcc, exec, s[0:1]
	s_cbranch_vccnz .LBB0_889
	s_barrier
	s_branch .LBB0_889
